# nt hint on final-norm streaming loads/stores
# speedup vs baseline: 1.1400x; 1.0014x over previous
.LBB0_1535:
	global_load_dwordx2 v[14:15], v1, s[2:3]
	global_load_dwordx2 v[16:17], v[6:7], off offset:-1024 nt
	global_load_dwordx4 v[10:13], v[2:3], off
	s_add_i32 s10, s10, s88
	s_add_u32 s2, s2, s4
	s_addc_u32 s3, s3, s5
	s_cmpk_gt_i32 s10, 0x3fff
	s_waitcnt vmcnt(0)
	v_ffbh_u32_e32 v9, v15
	v_min_u32_e32 v9, 32, v9
	v_lshlrev_b64 v[14:15], v9, v[14:15]
	v_min_u32_e32 v14, 1, v14
	v_or_b32_e32 v14, v15, v14
	v_cvt_f32_u32_e32 v14, v14
	v_sub_u32_e32 v9, 32, v9
	s_waitcnt vmcnt(1)
	v_lshlrev_b32_e32 v18, 16, v16
	v_and_b32_e32 v19, 0xffff0000, v16
	v_ldexp_f32 v9, v14, v9
	v_mul_f32_e32 v9, 0x35800000, v9
	v_fmamk_f32 v9, v9, 0x3a800000, v8
	v_mul_f32_e32 v14, 0x4f800000, v9
	v_cmp_gt_f32_e32 vcc, s11, v9
	v_lshlrev_b32_e32 v16, 16, v17
	v_and_b32_e32 v17, 0xffff0000, v17
	v_cndmask_b32_e32 v9, v9, v14, vcc
	v_sqrt_f32_e32 v14, v9
	s_nop 0
	v_add_u32_e32 v15, -1, v14
	v_add_u32_e32 v20, 1, v14
	v_fma_f32 v21, -v15, v14, v9
	v_fma_f32 v22, -v20, v14, v9
	v_cmp_ge_f32_e64 s[0:1], 0, v21
	s_nop 1
	v_cndmask_b32_e64 v14, v14, v15, s[0:1]
	v_cmp_lt_f32_e64 s[0:1], 0, v22
	s_nop 1
	v_cndmask_b32_e64 v14, v14, v20, s[0:1]
	v_mul_f32_e32 v15, 0x37800000, v14
	v_cndmask_b32_e32 v14, v14, v15, vcc
	v_cmp_class_f32_e32 vcc, v9, v0
	s_nop 1
	v_cndmask_b32_e32 v9, v14, v9, vcc
	v_div_scale_f32 v14, s[0:1], v9, v9, 1.0
	v_rcp_f32_e32 v20, v14
	v_div_scale_f32 v15, vcc, 1.0, v9, 1.0
	v_fma_f32 v21, -v14, v20, 1.0
	v_fmac_f32_e32 v20, v21, v20
	v_mul_f32_e32 v21, v15, v20
	v_fma_f32 v22, -v14, v21, v15
	v_fmac_f32_e32 v21, v22, v20
	v_fma_f32 v14, -v14, v21, v15
	v_div_fmas_f32 v14, v14, v20, v21
	v_div_fixup_f32 v14, v14, v9, 1.0
	v_pk_mul_f32 v[18:19], v[14:15], v[18:19] op_sel_hi:[0,1]
	v_pk_mul_f32 v[16:17], v[14:15], v[16:17] op_sel_hi:[0,1]
	s_waitcnt vmcnt(0)
	v_pk_mul_f32 v[12:13], v[12:13], v[16:17]
	v_pk_mul_f32 v[10:11], v[10:11], v[18:19]
	flat_store_dwordx4 v[4:5], v[10:13] nt
	global_load_dwordx2 v[16:17], v[6:7], off offset:-512 nt
	s_nop 0
	global_load_dwordx4 v[10:13], v[2:3], off offset:1024
	s_waitcnt vmcnt(0)
	v_lshlrev_b32_e32 v18, 16, v16
	v_and_b32_e32 v19, 0xffff0000, v16
	v_lshlrev_b32_e32 v16, 16, v17
	v_and_b32_e32 v17, 0xffff0000, v17
	v_pk_mul_f32 v[18:19], v[14:15], v[18:19] op_sel_hi:[0,1]
	v_pk_mul_f32 v[16:17], v[14:15], v[16:17] op_sel_hi:[0,1]
	v_pk_mul_f32 v[12:13], v[12:13], v[16:17]
	v_pk_mul_f32 v[10:11], v[10:11], v[18:19]
	flat_store_dwordx4 v[4:5], v[10:13] offset:1024 nt
	global_load_dwordx2 v[16:17], v[6:7], off nt
	s_nop 0
	global_load_dwordx4 v[10:13], v[2:3], off offset:2048
	s_waitcnt vmcnt(0)
	v_lshlrev_b32_e32 v18, 16, v16
	v_and_b32_e32 v19, 0xffff0000, v16
	v_lshlrev_b32_e32 v16, 16, v17
	v_and_b32_e32 v17, 0xffff0000, v17
	v_pk_mul_f32 v[18:19], v[14:15], v[18:19] op_sel_hi:[0,1]
	v_pk_mul_f32 v[16:17], v[14:15], v[16:17] op_sel_hi:[0,1]
	v_pk_mul_f32 v[12:13], v[12:13], v[16:17]
	v_pk_mul_f32 v[10:11], v[10:11], v[18:19]
	flat_store_dwordx4 v[4:5], v[10:13] offset:2048 nt
	global_load_dwordx2 v[16:17], v[6:7], off offset:512 nt
	s_nop 0
	global_load_dwordx4 v[10:13], v[2:3], off offset:3072
	v_lshl_add_u64 v[6:7], v[6:7], 0, s[8:9]
	s_waitcnt vmcnt(0)
	v_lshlrev_b32_e32 v18, 16, v16
	v_and_b32_e32 v19, 0xffff0000, v16
	v_lshlrev_b32_e32 v16, 16, v17
	v_and_b32_e32 v17, 0xffff0000, v17
	v_pk_mul_f32 v[18:19], v[14:15], v[18:19] op_sel_hi:[0,1]
	v_pk_mul_f32 v[14:15], v[14:15], v[16:17] op_sel_hi:[0,1]
	v_pk_mul_f32 v[12:13], v[12:13], v[14:15]
	v_pk_mul_f32 v[10:11], v[10:11], v[18:19]
	flat_store_dwordx4 v[4:5], v[10:13] offset:3072 nt
	v_lshl_add_u64 v[4:5], v[4:5], 0, s[6:7]
	s_cbranch_scc0 .LBB0_1535
